# stack + combine phase software-pipelined: a token's eight loads issued one iteration ahead into a second register set
# speedup vs baseline: 1.0022x; 1.0022x over previous
.LBB0_462:
	s_or_b64 exec, exec, s[0:1]
	v_readlane_b32 s2, v251, 28
	v_readlane_b32 s3, v251, 29
	s_andn2_b64 vcc, exec, s[2:3]
	s_waitcnt lgkmcnt(0)
	v_cndmask_b32_e64 v0, 0, 1, s[2:3]
	v_cmp_ne_u32_e64 s[0:1], 1, v0
	s_barrier
	s_nop 0
	v_writelane_b32 v250, s0, 33
	s_nop 1
	v_writelane_b32 v250, s1, 34
	s_cbranch_vccnz .LBB0_473
	v_readlane_b32 s0, v251, 47
	v_ashrrev_i32_e32 v4, 2, v168
	v_readlane_b32 s1, v251, 48
	s_mov_b32 s26, s0
	s_ashr_i32 s27, s0, 31
	v_lshlrev_b32_e32 v2, 6, v4
	v_lshlrev_b32_e32 v6, 4, v168
	s_lshl_b64 s[0:1], s[26:27], 11
	v_and_b32_e32 v0, 3, v168
	s_lshl_b64 s[2:3], s[26:27], 10
	v_ashrrev_i32_e32 v5, 31, v4
	v_ashrrev_i32_e32 v3, 31, v2
	v_lshl_or_b32 v0, v0, 5, s0
	v_mov_b32_e32 v1, s1
	s_ashr_i32 s93, s92, 31
	v_and_or_b32 v6, v6, 48, s2
	v_mov_b32_e32 v7, s3
	s_lshl_b64 s[6:7], s[26:27], 6
	s_mov_b32 s8, s26
	v_lshl_add_u64 v[0:1], v[2:3], 1, v[0:1]
	s_lshl_b64 s[0:1], s[92:93], 11
	v_lshl_add_u64 v[2:3], v[6:7], 0, v[2:3]
	s_lshl_b64 s[2:3], s[92:93], 10
	v_lshl_add_u64 v[4:5], v[4:5], 2, s[6:7]
	s_lshl_b64 s[6:7], s[92:93], 6
	v_readlane_b32 s93, v251, 49
	s_mov_b32 s10, 0xff800000
	v_writelane_b32 v251, s8, 47
	s_mov_b32 s11, s26
	s_nop 0
	v_writelane_b32 v251, s9, 48
	v_lshl_add_u64 v[6:7], s[20:21], 0, v[4:5]
	v_add_co_u32_e32 v8, vcc, 0x1f100000, v6
	s_nop 1
	v_addc_co_u32_e32 v9, vcc, 0, v7, vcc
	v_add_co_u32_e32 v10, vcc, 0x1f300000, v6
	s_nop 1
	v_addc_co_u32_e32 v11, vcc, 0, v7, vcc
	v_add_co_u32_e32 v12, vcc, 0x1f500000, v6
	s_nop 1
	v_addc_co_u32_e32 v13, vcc, 0, v7, vcc
	v_add_co_u32_e32 v6, vcc, 0x1f700000, v6
	s_nop 1
	v_addc_co_u32_e32 v7, vcc, 0, v7, vcc
	global_load_dword v134, v[8:9], off
	global_load_dword v135, v[10:11], off
	global_load_dword v136, v[12:13], off
	global_load_dword v137, v[6:7], off
	v_lshl_add_u64 v[62:63], s[20:21], 0, v[2:3]
	v_add_co_u32_e32 v116, vcc, 0x13100000, v62
	s_nop 1
	v_addc_co_u32_e32 v117, vcc, 0, v63, vcc
	global_load_dwordx4 v[116:119], v[116:117], off
	v_add_co_u32_e32 v120, vcc, 0x15100000, v62
	s_nop 1
	v_addc_co_u32_e32 v121, vcc, 0, v63, vcc
	global_load_dwordx4 v[120:123], v[120:121], off
	v_add_co_u32_e32 v124, vcc, 0x17100000, v62
	s_nop 1
	v_addc_co_u32_e32 v125, vcc, 0, v63, vcc
	global_load_dwordx4 v[124:127], v[124:125], off
	v_lshl_add_u64 v[128:129], s[18:19], 0, v[2:3]
	global_load_dwordx4 v[128:131], v[128:129], off
	v_lshl_add_u64 v[2:3], v[2:3], 0, s[2:3]
	v_lshl_add_u64 v[4:5], v[4:5], 0, s[6:7]
	s_waitcnt vmcnt(0)
	s_branch .LBB0_465

.LBB0_465:
	s_waitcnt vmcnt(2)
	v_mov_b32_e32 v14, v134
	v_mov_b32_e32 v27, v135
	v_mov_b32_e32 v26, v136
	v_mov_b32_e32 v24, v137
	v_mov_b64_e32 v[46:47], v[116:117]
	v_mov_b64_e32 v[48:49], v[118:119]
	v_mov_b64_e32 v[50:51], v[120:121]
	v_mov_b64_e32 v[52:53], v[122:123]
	v_mov_b64_e32 v[54:55], v[124:125]
	v_mov_b64_e32 v[56:57], v[126:127]
	v_mov_b64_e32 v[58:59], v[128:129]
	v_mov_b64_e32 v[60:61], v[130:131]
	v_lshl_add_u64 v[6:7], s[20:21], 0, v[4:5]
	v_add_co_u32_e32 v8, vcc, 0x1f100000, v6
	s_nop 1
	v_addc_co_u32_e32 v9, vcc, 0, v7, vcc
	v_add_co_u32_e32 v10, vcc, 0x1f300000, v6
	s_nop 1
	v_addc_co_u32_e32 v11, vcc, 0, v7, vcc
	v_add_co_u32_e32 v12, vcc, 0x1f500000, v6
	s_nop 1
	v_addc_co_u32_e32 v13, vcc, 0, v7, vcc
	v_add_co_u32_e32 v6, vcc, 0x1f700000, v6
	s_nop 1
	v_addc_co_u32_e32 v7, vcc, 0, v7, vcc
	global_load_dword v134, v[8:9], off
	global_load_dword v135, v[10:11], off
	global_load_dword v136, v[12:13], off
	global_load_dword v137, v[6:7], off
	v_lshl_add_u64 v[62:63], s[20:21], 0, v[2:3]
	v_add_co_u32_e32 v116, vcc, 0x13100000, v62
	s_nop 1
	v_addc_co_u32_e32 v117, vcc, 0, v63, vcc
	global_load_dwordx4 v[116:119], v[116:117], off
	v_add_co_u32_e32 v120, vcc, 0x15100000, v62
	s_nop 1
	v_addc_co_u32_e32 v121, vcc, 0, v63, vcc
	global_load_dwordx4 v[120:123], v[120:121], off
	v_add_co_u32_e32 v124, vcc, 0x17100000, v62
	s_nop 1
	v_addc_co_u32_e32 v125, vcc, 0, v63, vcc
	global_load_dwordx4 v[124:127], v[124:125], off
	v_lshl_add_u64 v[128:129], s[18:19], 0, v[2:3]
	global_load_dwordx4 v[128:131], v[128:129], off
	v_mov_b32_e32 v16, 0
	v_mov_b32_e32 v17, v16
	v_mov_b64_e32 v[18:19], v[16:17]
	v_mov_b64_e32 v[20:21], v[16:17]
	v_mov_b64_e32 v[6:7], v[16:17]
	v_mov_b64_e32 v[8:9], v[16:17]
	v_mov_b64_e32 v[10:11], v[16:17]
	v_mov_b64_e32 v[12:13], v[16:17]
	v_mov_b64_e32 v[22:23], v[16:17]
	v_max3_f32 v15, v14, s10, v27
	v_max3_f32 v25, v15, v26, v24
	v_sub_f32_e32 v14, v14, v25
	v_exp_f32_e32 v28, v14
	v_mov_b64_e32 v[14:15], v[16:17]
	v_cmp_lt_f32_e32 vcc, 0, v28
	s_and_saveexec_b64 s[8:9], vcc
	s_cbranch_execz .LBB0_467
	v_mul_f32_e32 v16, 0x3d800000, v28
	v_cvt_pk_f32_fp8_e32 v[10:11], v46
	v_cvt_pk_f32_fp8_sdwa v[12:13], v46 src0_sel:WORD_1
	v_cvt_pk_f32_fp8_e32 v[14:15], v47
	v_cvt_pk_f32_fp8_sdwa v[6:7], v47 src0_sel:WORD_1
	v_cvt_pk_f32_fp8_e32 v[30:31], v48
	v_cvt_pk_f32_fp8_sdwa v[32:33], v48 src0_sel:WORD_1
	v_cvt_pk_f32_fp8_e32 v[34:35], v49
	v_cvt_pk_f32_fp8_sdwa v[36:37], v49 src0_sel:WORD_1
	v_pk_fma_f32 v[22:23], v[16:17], v[10:11], 0 op_sel_hi:[0,1,0]
	v_pk_fma_f32 v[20:21], v[16:17], v[12:13], 0 op_sel_hi:[0,1,0]
	v_pk_fma_f32 v[18:19], v[16:17], v[14:15], 0 op_sel_hi:[0,1,0]
	v_pk_fma_f32 v[14:15], v[16:17], v[6:7], 0 op_sel_hi:[0,1,0]
	v_pk_fma_f32 v[12:13], v[16:17], v[30:31], 0 op_sel_hi:[0,1,0]
	v_pk_fma_f32 v[10:11], v[16:17], v[32:33], 0 op_sel_hi:[0,1,0]
	v_pk_fma_f32 v[8:9], v[16:17], v[34:35], 0 op_sel_hi:[0,1,0]
	v_pk_fma_f32 v[6:7], v[16:17], v[36:37], 0 op_sel_hi:[0,1,0]
	v_mov_b32_e32 v16, v28
.LBB0_467:
	s_or_b64 exec, exec, s[8:9]
	v_sub_f32_e32 v17, v27, v25
	v_exp_f32_e32 v17, v17
	s_nop 0
	v_cmp_lt_f32_e32 vcc, 0, v17
	s_and_saveexec_b64 s[8:9], vcc
	s_cbranch_execz .LBB0_469
	v_mul_f32_e32 v32, 0x3d800000, v17
	v_add_f32_e32 v16, v16, v17
	v_cvt_pk_f32_fp8_e32 v[34:35], v50
	v_cvt_pk_f32_fp8_sdwa v[36:37], v50 src0_sel:WORD_1
	v_cvt_pk_f32_fp8_e32 v[38:39], v51
	v_cvt_pk_f32_fp8_sdwa v[28:29], v51 src0_sel:WORD_1
	v_cvt_pk_f32_fp8_e32 v[40:41], v52
	v_cvt_pk_f32_fp8_sdwa v[42:43], v52 src0_sel:WORD_1
	v_cvt_pk_f32_fp8_e32 v[44:45], v53
	v_cvt_pk_f32_fp8_sdwa v[30:31], v53 src0_sel:WORD_1
	v_pk_fma_f32 v[22:23], v[32:33], v[34:35], v[22:23] op_sel_hi:[0,1,1]
	v_pk_fma_f32 v[20:21], v[32:33], v[36:37], v[20:21] op_sel_hi:[0,1,1]
	v_pk_fma_f32 v[18:19], v[32:33], v[38:39], v[18:19] op_sel_hi:[0,1,1]
	v_pk_fma_f32 v[14:15], v[32:33], v[28:29], v[14:15] op_sel_hi:[0,1,1]
	v_pk_fma_f32 v[12:13], v[32:33], v[40:41], v[12:13] op_sel_hi:[0,1,1]
	v_pk_fma_f32 v[10:11], v[32:33], v[42:43], v[10:11] op_sel_hi:[0,1,1]
	v_pk_fma_f32 v[8:9], v[32:33], v[44:45], v[8:9] op_sel_hi:[0,1,1]
	v_pk_fma_f32 v[6:7], v[32:33], v[30:31], v[6:7] op_sel_hi:[0,1,1]
.LBB0_469:
	s_or_b64 exec, exec, s[8:9]
	v_sub_f32_e32 v17, v26, v25
	v_exp_f32_e32 v17, v17
	s_nop 0
	v_cmp_lt_f32_e32 vcc, 0, v17
	s_and_saveexec_b64 s[8:9], vcc
	s_cbranch_execz .LBB0_471
	v_mul_f32_e32 v30, 0x3d800000, v17
	v_add_f32_e32 v16, v16, v17
	v_cvt_pk_f32_fp8_e32 v[32:33], v54
	v_cvt_pk_f32_fp8_sdwa v[34:35], v54 src0_sel:WORD_1
	v_cvt_pk_f32_fp8_e32 v[36:37], v55
	v_cvt_pk_f32_fp8_sdwa v[26:27], v55 src0_sel:WORD_1
	v_cvt_pk_f32_fp8_e32 v[38:39], v56
	v_cvt_pk_f32_fp8_sdwa v[40:41], v56 src0_sel:WORD_1
	v_cvt_pk_f32_fp8_e32 v[42:43], v57
	v_cvt_pk_f32_fp8_sdwa v[28:29], v57 src0_sel:WORD_1
	v_pk_fma_f32 v[22:23], v[30:31], v[32:33], v[22:23] op_sel_hi:[0,1,1]
	v_pk_fma_f32 v[20:21], v[30:31], v[34:35], v[20:21] op_sel_hi:[0,1,1]
	v_pk_fma_f32 v[18:19], v[30:31], v[36:37], v[18:19] op_sel_hi:[0,1,1]
	v_pk_fma_f32 v[14:15], v[30:31], v[26:27], v[14:15] op_sel_hi:[0,1,1]
	v_pk_fma_f32 v[12:13], v[30:31], v[38:39], v[12:13] op_sel_hi:[0,1,1]
	v_pk_fma_f32 v[10:11], v[30:31], v[40:41], v[10:11] op_sel_hi:[0,1,1]
	v_pk_fma_f32 v[8:9], v[30:31], v[42:43], v[8:9] op_sel_hi:[0,1,1]
	v_pk_fma_f32 v[6:7], v[30:31], v[28:29], v[6:7] op_sel_hi:[0,1,1]
.LBB0_471:
	s_or_b64 exec, exec, s[8:9]
	v_sub_f32_e32 v17, v24, v25
	v_exp_f32_e32 v17, v17
	s_nop 0
	v_cmp_lt_f32_e32 vcc, 0, v17
	s_and_saveexec_b64 s[8:9], vcc
	s_cbranch_execz .LBB0_464
	v_mul_f32_e32 v28, 0x3d800000, v17
	v_add_f32_e32 v16, v16, v17
	v_cvt_pk_f32_fp8_e32 v[30:31], v58
	v_cvt_pk_f32_fp8_sdwa v[32:33], v58 src0_sel:WORD_1
	v_cvt_pk_f32_fp8_e32 v[34:35], v59
	v_cvt_pk_f32_fp8_sdwa v[24:25], v59 src0_sel:WORD_1
	v_cvt_pk_f32_fp8_e32 v[36:37], v60
	v_cvt_pk_f32_fp8_sdwa v[38:39], v60 src0_sel:WORD_1
	v_cvt_pk_f32_fp8_e32 v[40:41], v61
	v_cvt_pk_f32_fp8_sdwa v[26:27], v61 src0_sel:WORD_1
	v_pk_fma_f32 v[22:23], v[28:29], v[30:31], v[22:23] op_sel_hi:[0,1,1]
	v_pk_fma_f32 v[20:21], v[28:29], v[32:33], v[20:21] op_sel_hi:[0,1,1]
	v_pk_fma_f32 v[18:19], v[28:29], v[34:35], v[18:19] op_sel_hi:[0,1,1]
	v_pk_fma_f32 v[14:15], v[28:29], v[24:25], v[14:15] op_sel_hi:[0,1,1]
	v_pk_fma_f32 v[12:13], v[28:29], v[36:37], v[12:13] op_sel_hi:[0,1,1]
	v_pk_fma_f32 v[10:11], v[28:29], v[38:39], v[10:11] op_sel_hi:[0,1,1]
	v_pk_fma_f32 v[8:9], v[28:29], v[40:41], v[8:9] op_sel_hi:[0,1,1]
	v_pk_fma_f32 v[6:7], v[28:29], v[26:27], v[6:7] op_sel_hi:[0,1,1]
	s_branch .LBB0_464
